# P1/P5 GEMM phases: one static s_setprio 1 for the younger half (waves 4-7), per-MFMA-block priority flips deleted
# speedup vs baseline: 1.0132x; 1.0132x over previous
; #define PG8_STAGE(bufoff, gbase, voff) do { _Pragma("unroll") for (int _i = 0; _i < 2; ++_i) \
;         __builtin_amdgcn_global_load_lds((const unsigned*)((const char*)(gbase) + (voff)[_i]), (PG8_LAS unsigned*)(lds + (bufoff) + ldsw + _i * 8192), 16, 0, 0); } while (0)
; #define PG8_BAR __builtin_amdgcn_s_barrier()
; template <class Epi, class Sched, bool ALIGN_EPI = false, bool SP2 = false, bool SPLITK = false>
; __device__ __forceinline__ void gemm_phase(PG8_LAS unsigned char* lds, const Gemm g, const Sched& S, const Epi& E) {
;     ...
;     for (int i = 0; i < 2; ++i) { int R, C; stage_rc(tid * 16 + i * 8192, R, C); const int Rb = Epi::PERM ? ((R & ~31) + perm32(R & 31)) : R;
;         voffA[i] = (unsigned)(R * K + C) * 2u; voffB[i] = (unsigned)(Rb * K + C) * 2u; }
;     ...
;     const char* cA = (const char*)g.A + (size_t)cur.pm * tstep; const char* cB = (const char*)g.Bt + (size_t)cur.pn * tstep;
;     const char* cA2 = SPLITK ? (const char*)g.A2 + (size_t)cur.pm * tstep : cA; const char* cB2 = SPLITK ? (const char*)g.Bt2 + (size_t)cur.pn * tstep : cB;
;     ...
;     S.a_ready(cur);
;     if constexpr (SP2) {
;         PG8_STAGE(PG8_SB(0, 0), cB, voffB); PG8_STAGE(PG8_SB(0, 1), cB + hstep, voffB); PG8_STAGE(PG8_SA(0, 0), cA, voffA); PG8_STAGE(PG8_SA(0, 1), cA + hstep, voffA);
;         PG8_STAGE(PG8_SB(1, 0), cB + kstep, voffB); PG8_STAGE(PG8_SA(1, 0), cA + kstep, voffA); PG8_STAGE(PG8_SB(1, 1), cB + hstep + kstep, voffB);
;         if (wr == 1) PG8_BAR;
.LBB0_152:
	s_mul_i32 s3, s92, 0x2680000
	v_readlane_b32 s16, v253, 48
	s_mul_hi_u32 s2, s92, 0x2680000
	v_readlane_b32 s17, v253, 49
	s_add_u32 s3, s16, s3
	v_writelane_b32 v255, s3, 45
	s_addc_u32 s2, s17, s2
	v_writelane_b32 v255, s2, 46
	s_and_b64 vcc, exec, s[38:39]
	s_cbranch_vccnz .LBB0_192
	v_ashrrev_i32_e32 v0, 31, v2
	v_lshrrev_b32_e32 v0, 26, v0
	v_add_u32_e32 v0, v2, v0
	v_ashrrev_i32_e32 v3, 6, v0
	v_bfe_i32 v0, v2, 27, 1
	v_lshlrev_b32_e32 v6, 4, v2
	v_lshrrev_b32_e32 v0, 22, v0
	v_add_u32_e32 v0, v6, v0
	v_and_b32_e32 v0, 0xfffffc00, v0
	v_sub_u32_e32 v0, v6, v0
	v_lshrrev_b32_e32 v4, 4, v0
	v_bitop3_b32 v0, v4, v0, 32 bitop3:0x6c
	v_lshlrev_b32_e32 v4, 3, v3
	v_and_b32_e32 v5, -16, v4
	v_ashrrev_i32_e32 v4, 31, v0
	v_lshrrev_b32_e32 v4, 26, v4
	v_add_u32_e32 v7, v0, v4
	v_ashrrev_i32_e32 v4, 6, v7
	v_add_u32_e32 v8, v4, v5
	v_lshlrev_b32_e32 v5, 5, v3
	v_and_b32_e32 v9, 32, v5
	v_and_b32_e32 v5, 0xc0, v7
	v_sub_u32_e32 v0, v0, v5
	v_ashrrev_i16_sdwa v0, v234, sext(v0) dst_sel:DWORD dst_unused:UNUSED_PAD src0_sel:DWORD src1_sel:BYTE_0
	v_bfe_i32 v5, v0, 0, 16
	v_lshlrev_b32_e32 v0, 1, v8
	v_lshrrev_b32_e32 v7, 2, v8
	v_and_b32_e32 v10, 3, v4
	s_mov_b32 s2, 0x1fffe0
	v_and_b32_e32 v0, 24, v0
	v_and_b32_e32 v7, 4, v7
	v_and_or_b32 v10, v8, s2, v10
	v_or3_b32 v0, v10, v7, v0
	v_add_lshl_u32 v7, v9, v5, 1
	v_lshl_add_u32 v168, v8, 11, v7
	v_lshl_add_u32 v0, v0, 11, v7
	v_add_u32_e32 v7, 0x2000, v6
	v_ashrrev_i32_e32 v6, 31, v7
	v_lshrrev_b32_e32 v6, 22, v6
	v_add_u32_e32 v6, v7, v6
	v_ashrrev_i32_e32 v6, 10, v6
	v_mul_i32_i24_e32 v8, 0x400, v6
	v_sub_u32_e32 v7, v7, v8
	v_lshrrev_b32_e32 v8, 4, v7
	v_bitop3_b32 v8, v8, v7, 32 bitop3:0x6c
	v_lshlrev_b32_e32 v7, 3, v6
	v_and_b32_e32 v9, -16, v7
	v_ashrrev_i32_e32 v7, 31, v8
	v_lshrrev_b32_e32 v7, 26, v7
	v_add_u32_e32 v10, v8, v7
	v_ashrrev_i32_e32 v7, 6, v10
	s_ashr_i32 s12, s4, 6
	v_add_u32_e32 v9, v7, v9
	v_and_b32_e32 v13, 3, v7
	s_ashr_i32 s53, s52, 31
	s_ashr_i32 s43, s42, 31
	v_and_b32_e32 v10, 0xc0, v10
	v_and_or_b32 v13, v9, s2, v13
	s_ashr_i32 s20, s4, 8
	s_lshl_b32 s33, s12, 10
	s_lshl_b64 s[2:3], s[52:53], 19
	s_lshl_b64 s[16:17], s[42:43], 19
	v_readlane_b32 s18, v255, 45
	v_sub_u32_e32 v8, v8, v10
	s_add_u32 s46, s18, s16
	v_readlane_b32 s16, v255, 46
	v_lshlrev_b32_e32 v11, 5, v6
	v_ashrrev_i16_sdwa v8, v234, sext(v8) dst_sel:DWORD dst_unused:UNUSED_PAD src0_sel:DWORD src1_sel:BYTE_0
	v_lshlrev_b32_e32 v10, 1, v9
	v_lshrrev_b32_e32 v12, 2, v9
	s_addc_u32 s47, s16, s17
	s_add_i32 s51, s33, 0
	v_and_b32_e32 v11, 32, v11
	v_bfe_i32 v8, v8, 0, 16
	v_and_b32_e32 v10, 24, v10
	v_and_b32_e32 v12, 4, v12
	s_add_i32 m0, s51, 0x10000
	v_or3_b32 v10, v13, v12, v10
	v_add_lshl_u32 v11, v11, v8, 1
	global_load_lds_dwordx4 v0, s[46:47]
	s_add_i32 m0, s51, 0x12000
	v_lshl_add_u32 v172, v10, 11, v11
	s_add_u32 s16, s46, 0x40000
	global_load_lds_dwordx4 v172, s[46:47]
	s_addc_u32 s17, s47, 0
	s_add_i32 m0, s51, 0x14000
	v_lshl_add_u32 v170, v9, 11, v11
	global_load_lds_dwordx4 v0, s[16:17]
	s_add_i32 m0, s51, 0x16000
	s_add_u32 s48, s82, s2
	s_addc_u32 s49, s83, s3
	s_add_i32 s53, s51, 0x2000
	global_load_lds_dwordx4 v172, s[16:17]
	s_mov_b32 m0, s51
	s_add_u32 s2, s48, 0x40000
	global_load_lds_dwordx4 v168, s[48:49]
	s_mov_b32 m0, s53
	s_addc_u32 s3, s49, 0
	s_add_i32 s56, s51, 0x4000
	global_load_lds_dwordx4 v170, s[48:49]
	s_mov_b32 m0, s56
	s_add_i32 s57, s51, 0x6000
	v_lshl_add_u64 v[10:11], s[46:47], 0, v[0:1]
	v_mov_b32_e32 v173, v1
	global_load_lds_dwordx4 v168, s[2:3]
	s_mov_b32 m0, s57
	v_lshl_add_u64 v[12:13], s[46:47], 0, v[172:173]
	v_mov_b32_e32 v169, v1
	global_load_lds_dwordx4 v170, s[2:3]
	s_add_i32 m0, s51, 0x18000
	v_lshl_add_u64 v[10:11], v[10:11], 0, s[70:71]
	v_lshl_add_u64 v[14:15], s[48:49], 0, v[168:169]
	v_mov_b32_e32 v171, v1
	global_load_lds_dwordx4 v[10:11], off
	v_lshl_add_u64 v[10:11], v[12:13], 0, s[70:71]
	s_add_i32 m0, s51, 0x1a000
	s_add_i32 s58, s51, 0x8000
	v_lshl_add_u64 v[16:17], s[48:49], 0, v[170:171]
	global_load_lds_dwordx4 v[10:11], off
	v_lshl_add_u64 v[10:11], v[14:15], 0, s[70:71]
	s_mov_b32 m0, s58
	s_add_i32 s59, s51, 0xa000
	global_load_lds_dwordx4 v[10:11], off
	v_lshl_add_u64 v[10:11], v[16:17], 0, s[70:71]
	s_mov_b32 m0, s59
	s_add_u32 s2, s46, 0x40080
	global_load_lds_dwordx4 v[10:11], off
	s_addc_u32 s3, s47, 0
	s_add_i32 m0, s51, 0x1c000
	s_nop 0
	global_load_lds_dwordx4 v0, s[2:3]
	s_add_i32 m0, s51, 0x1e000
	s_cmp_eq_u32 s20, 1
	global_load_lds_dwordx4 v172, s[2:3]
	s_cselect_b64 s[2:3], -1, 0
	s_cmp_lg_u32 s20, 1
	s_cbranch_scc1 .LBB0_155
	s_setprio 1
	s_barrier

; #define PG8_STAGE(bufoff, gbase, voff) do { _Pragma("unroll") for (int _i = 0; _i < 2; ++_i) \
;         __builtin_amdgcn_global_load_lds((const unsigned*)((const char*)(gbase) + (voff)[_i]), (PG8_LAS unsigned*)(lds + (bufoff) + ldsw + _i * 8192), 16, 0, 0); } while (0)
; #define PG8_LDA(dst, b, h) do { _Pragma("unroll") for (int m = 0; m < 4; ++m) _Pragma("unroll") for (int k = 0; k < 2; ++k) dst[m][k] = *(const PG8_LAS bf16x8*)(lds + PG8_SA(b, h) + aoff + m * 2048 + k * 1024); } while (0)
; #define PG8_LDB(dst, b, h) do { _Pragma("unroll") for (int n = 0; n < 2; ++n) _Pragma("unroll") for (int k = 0; k < 2; ++k) dst[n][k] = *(const PG8_LAS bf16x8*)(lds + PG8_SB(b, h) + boff + n * 2048 + k * 1024); } while (0)
; #define PG8_MMA(ai, bj, At, Bt) do { __builtin_amdgcn_s_setprio(1); _Pragma("unroll") for (int m = 0; m < 4; ++m) _Pragma("unroll") for (int n = 0; n < 2; ++n) _Pragma("unroll") for (int k = 0; k < 2; ++k) \
;         acc[ai][bj][m][n] = __builtin_amdgcn_mfma_f32_16x16x32_bf16(Bt[n][k], At[m][k], acc[ai][bj][m][n], 0, 0, 0); __builtin_amdgcn_s_setprio(0); } while (0)
; #define PG8_WAIT_V(n) asm volatile("s_waitcnt vmcnt(" #n ")" ::: "memory")
; #define PG8_WAIT_L(n) asm volatile("s_waitcnt lgkmcnt(" #n ")" ::: "memory")
; #define PG8_BAR __builtin_amdgcn_s_barrier()
; #define PG8_SCHED __builtin_amdgcn_sched_barrier(0)
; template <class Epi, class Sched, bool ALIGN_EPI = false, bool SP2 = false, bool SPLITK = false>
; __device__ __forceinline__ void gemm_phase(PG8_LAS unsigned char* lds, const Gemm g, const Sched& S, const Epi& E) {
;     ...
;             PG8_LDB(B0, 0, 0); PG8_LDB(B1, 0, 1); PG8_SCHED; PG8_LDA(At, 0, 0); PG8_STAGE(PG8_SA(1, 1), a1 + hstep, voffA);
;             PG8_WAIT_V(8); PG8_WAIT_L(0); PG8_BAR; PG8_MMA(0, 0, At, B0); PG8_MMA(0, 1, At, B1); PG8_BAR; PG8_SCHED;
;             PG8_LDA(At, 0, 1); PG8_STAGE(PG8_SB(0, 0), b2, voffB); PG8_STAGE(PG8_SB(0, 1), b2 + hstep, voffB); PG8_STAGE(PG8_SA(0, 0), a2, voffA);
;             PG8_WAIT_V(8); PG8_WAIT_L(0); PG8_BAR; PG8_MMA(1, 0, At, B0); PG8_MMA(1, 1, At, B1); PG8_BAR; PG8_SCHED;
.LBB0_165:
	s_add_u32 s35, s54, 0xfffc0080
	s_addc_u32 s43, s55, -1
	s_add_i32 s45, 0, 0x10000
	s_cmp_eq_u32 s25, 12
	s_cselect_b32 s49, s4, s43
	s_cselect_b32 s48, s12, s35
	s_cselect_b32 s47, s21, s24
	s_cselect_b32 s46, s22, s23
	s_add_i32 s35, 0, 0x14000
	v_add_u32_e32 v142, s45, v198
	v_add_u32_e32 v158, s35, v198
	ds_read_b128 v[130:133], v142
	ds_read_b128 v[134:137], v142 offset:1024
	ds_read_b128 v[138:141], v142 offset:2048
	ds_read_b128 v[142:145], v142 offset:3072
	ds_read_b128 v[146:149], v158
	ds_read_b128 v[150:153], v158 offset:1024
	ds_read_b128 v[154:157], v158 offset:2048
	ds_read_b128 v[158:161], v158 offset:3072
	s_add_i32 m0, s51, 0xc000
	ds_read_b128 v[162:165], v199
	ds_read_b128 v[178:181], v199 offset:1024
	ds_read_b128 v[182:185], v199 offset:2048
	ds_read_b128 v[186:189], v199 offset:3072
	ds_read_b128 v[190:193], v199 offset:4096
	ds_read_b128 v[200:203], v199 offset:5120
	ds_read_b128 v[204:207], v199 offset:6144
	ds_read_b128 v[208:211], v199 offset:7168
	global_load_lds_dwordx4 v174, s[54:55]
	s_add_i32 m0, s51, 0xe000
	s_nop 0
	global_load_lds_dwordx4 v176, s[54:55]
	s_waitcnt vmcnt(8)
	s_waitcnt lgkmcnt(0)
	s_barrier
	s_waitcnt lgkmcnt(0)
	v_mfma_f32_16x16x32_bf16 v[126:129], v[130:133], v[162:165], v[126:129]
	v_mfma_f32_16x16x32_bf16 v[122:125], v[138:141], v[162:165], v[122:125]
	v_mfma_f32_16x16x32_bf16 v[114:117], v[130:133], v[182:185], v[114:117]
	v_mfma_f32_16x16x32_bf16 v[106:109], v[138:141], v[182:185], v[106:109]
	v_mfma_f32_16x16x32_bf16 v[98:101], v[130:133], v[190:193], v[98:101]
	v_mfma_f32_16x16x32_bf16 v[90:93], v[138:141], v[190:193], v[90:93]
	v_mfma_f32_16x16x32_bf16 v[82:85], v[130:133], v[204:207], v[82:85]
	v_mfma_f32_16x16x32_bf16 v[74:77], v[138:141], v[204:207], v[74:77]
	v_mfma_f32_16x16x32_bf16 v[126:129], v[134:137], v[178:181], v[126:129]
	v_mfma_f32_16x16x32_bf16 v[122:125], v[142:145], v[178:181], v[122:125]
	v_mfma_f32_16x16x32_bf16 v[114:117], v[134:137], v[186:189], v[114:117]
	v_mfma_f32_16x16x32_bf16 v[106:109], v[142:145], v[186:189], v[106:109]
	v_mfma_f32_16x16x32_bf16 v[98:101], v[134:137], v[200:203], v[98:101]
	v_mfma_f32_16x16x32_bf16 v[90:93], v[142:145], v[200:203], v[90:93]
	v_mfma_f32_16x16x32_bf16 v[82:85], v[134:137], v[208:211], v[82:85]
	v_mfma_f32_16x16x32_bf16 v[74:77], v[142:145], v[208:211], v[74:77]
	v_mfma_f32_16x16x32_bf16 v[118:121], v[146:149], v[162:165], v[118:121]
	v_mfma_f32_16x16x32_bf16 v[110:113], v[154:157], v[162:165], v[110:113]
	v_mfma_f32_16x16x32_bf16 v[102:105], v[146:149], v[182:185], v[102:105]
	v_mfma_f32_16x16x32_bf16 v[94:97], v[154:157], v[182:185], v[94:97]
	v_mfma_f32_16x16x32_bf16 v[86:89], v[146:149], v[190:193], v[86:89]
	v_mfma_f32_16x16x32_bf16 v[78:81], v[154:157], v[190:193], v[78:81]
	v_mfma_f32_16x16x32_bf16 v[70:73], v[146:149], v[204:207], v[70:73]
	v_mfma_f32_16x16x32_bf16 v[66:69], v[154:157], v[204:207], v[66:69]
	v_mfma_f32_16x16x32_bf16 v[118:121], v[150:153], v[178:181], v[118:121]
	v_mfma_f32_16x16x32_bf16 v[110:113], v[158:161], v[178:181], v[110:113]
	v_mfma_f32_16x16x32_bf16 v[102:105], v[150:153], v[186:189], v[102:105]
	v_mfma_f32_16x16x32_bf16 v[94:97], v[158:161], v[186:189], v[94:97]
	v_mfma_f32_16x16x32_bf16 v[86:89], v[150:153], v[200:203], v[86:89]
	v_mfma_f32_16x16x32_bf16 v[78:81], v[158:161], v[200:203], v[78:81]
	v_mfma_f32_16x16x32_bf16 v[70:73], v[150:153], v[208:211], v[70:73]
	v_mfma_f32_16x16x32_bf16 v[66:69], v[158:161], v[208:211], v[66:69]
	s_barrier
	s_add_i32 s43, s45, s33
	s_mov_b32 m0, s43
	ds_read_b128 v[162:165], v199 offset:16384
	ds_read_b128 v[178:181], v199 offset:17408
	ds_read_b128 v[182:185], v199 offset:18432
	ds_read_b128 v[186:189], v199 offset:19456
	ds_read_b128 v[190:193], v199 offset:20480
	ds_read_b128 v[200:203], v199 offset:21504
	ds_read_b128 v[204:207], v199 offset:22528
	ds_read_b128 v[208:211], v199 offset:23552
	global_load_lds_dwordx4 v0, s[46:47]
	s_add_i32 m0, s43, 0x2000
	s_add_u32 s76, s46, 0x40000
	s_addc_u32 s77, s47, 0
	s_add_i32 s35, s35, s33
	global_load_lds_dwordx4 v172, s[46:47]
	s_mov_b32 m0, s35
	s_nop 0
	global_load_lds_dwordx4 v0, s[76:77]
	s_add_i32 m0, s35, 0x2000
	s_nop 0
	global_load_lds_dwordx4 v172, s[76:77]
	s_mov_b32 m0, s51
	s_nop 0
	global_load_lds_dwordx4 v168, s[48:49]
	s_mov_b32 m0, s53
	s_nop 0
	global_load_lds_dwordx4 v170, s[48:49]
	s_waitcnt vmcnt(8)
	s_waitcnt lgkmcnt(0)
	s_barrier
	s_waitcnt lgkmcnt(0)
	v_mfma_f32_16x16x32_bf16 v[62:65], v[130:133], v[162:165], v[62:65]
	v_mfma_f32_16x16x32_bf16 v[58:61], v[138:141], v[162:165], v[58:61]
	v_mfma_f32_16x16x32_bf16 v[50:53], v[130:133], v[182:185], v[50:53]
	v_mfma_f32_16x16x32_bf16 v[42:45], v[138:141], v[182:185], v[42:45]
	v_mfma_f32_16x16x32_bf16 v[34:37], v[130:133], v[190:193], v[34:37]
	v_mfma_f32_16x16x32_bf16 v[26:29], v[138:141], v[190:193], v[26:29]
	v_mfma_f32_16x16x32_bf16 v[18:21], v[130:133], v[204:207], v[18:21]
	v_mfma_f32_16x16x32_bf16 v[10:13], v[138:141], v[204:207], v[10:13]
	v_mfma_f32_16x16x32_bf16 v[62:65], v[134:137], v[178:181], v[62:65]
	v_mfma_f32_16x16x32_bf16 v[58:61], v[142:145], v[178:181], v[58:61]
	v_mfma_f32_16x16x32_bf16 v[50:53], v[134:137], v[186:189], v[50:53]
	v_mfma_f32_16x16x32_bf16 v[42:45], v[142:145], v[186:189], v[42:45]
	v_mfma_f32_16x16x32_bf16 v[34:37], v[134:137], v[200:203], v[34:37]
	v_mfma_f32_16x16x32_bf16 v[26:29], v[142:145], v[200:203], v[26:29]
	v_mfma_f32_16x16x32_bf16 v[18:21], v[134:137], v[208:211], v[18:21]
	v_mfma_f32_16x16x32_bf16 v[10:13], v[142:145], v[208:211], v[10:13]
	v_mfma_f32_16x16x32_bf16 v[54:57], v[146:149], v[162:165], v[54:57]
	v_mfma_f32_16x16x32_bf16 v[46:49], v[154:157], v[162:165], v[46:49]
	v_mfma_f32_16x16x32_bf16 v[38:41], v[146:149], v[182:185], v[38:41]
	v_mfma_f32_16x16x32_bf16 v[30:33], v[154:157], v[182:185], v[30:33]
	v_mfma_f32_16x16x32_bf16 v[22:25], v[146:149], v[190:193], v[22:25]
	v_mfma_f32_16x16x32_bf16 v[14:17], v[154:157], v[190:193], v[14:17]
	v_mfma_f32_16x16x32_bf16 v[6:9], v[146:149], v[204:207], v[6:9]
	v_mfma_f32_16x16x32_bf16 v[2:5], v[154:157], v[204:207], v[2:5]
	v_mfma_f32_16x16x32_bf16 v[54:57], v[150:153], v[178:181], v[54:57]
	v_mfma_f32_16x16x32_bf16 v[46:49], v[158:161], v[178:181], v[46:49]
	v_mfma_f32_16x16x32_bf16 v[38:41], v[150:153], v[186:189], v[38:41]
	v_mfma_f32_16x16x32_bf16 v[30:33], v[158:161], v[186:189], v[30:33]
	v_mfma_f32_16x16x32_bf16 v[22:25], v[150:153], v[200:203], v[22:25]
	v_mfma_f32_16x16x32_bf16 v[14:17], v[158:161], v[200:203], v[14:17]
	v_mfma_f32_16x16x32_bf16 v[6:9], v[150:153], v[208:211], v[6:9]
	v_mfma_f32_16x16x32_bf16 v[2:5], v[158:161], v[208:211], v[2:5]
	s_barrier
; #define PG8_STAGE(bufoff, gbase, voff) do { _Pragma("unroll") for (int _i = 0; _i < 2; ++_i) \
;         __builtin_amdgcn_global_load_lds((const unsigned*)((const char*)(gbase) + (voff)[_i]), (PG8_LAS unsigned*)(lds + (bufoff) + ldsw + _i * 8192), 16, 0, 0); } while (0)
; #define PG8_LDA(dst, b, h) do { _Pragma("unroll") for (int m = 0; m < 4; ++m) _Pragma("unroll") for (int k = 0; k < 2; ++k) dst[m][k] = *(const PG8_LAS bf16x8*)(lds + PG8_SA(b, h) + aoff + m * 2048 + k * 1024); } while (0)
; #define PG8_LDB(dst, b, h) do { _Pragma("unroll") for (int n = 0; n < 2; ++n) _Pragma("unroll") for (int k = 0; k < 2; ++k) dst[n][k] = *(const PG8_LAS bf16x8*)(lds + PG8_SB(b, h) + boff + n * 2048 + k * 1024); } while (0)
; #define PG8_MMA(ai, bj, At, Bt) do { __builtin_amdgcn_s_setprio(1); _Pragma("unroll") for (int m = 0; m < 4; ++m) _Pragma("unroll") for (int n = 0; n < 2; ++n) _Pragma("unroll") for (int k = 0; k < 2; ++k) \
;         acc[ai][bj][m][n] = __builtin_amdgcn_mfma_f32_16x16x32_bf16(Bt[n][k], At[m][k], acc[ai][bj][m][n], 0, 0, 0); __builtin_amdgcn_s_setprio(0); } while (0)
; #define PG8_WAIT_V(n) asm volatile("s_waitcnt vmcnt(" #n ")" ::: "memory")
; #define PG8_WAIT_L(n) asm volatile("s_waitcnt lgkmcnt(" #n ")" ::: "memory")
; #define PG8_BAR __builtin_amdgcn_s_barrier()
; #define PG8_SCHED __builtin_amdgcn_sched_barrier(0)
; template <class Epi, class Sched, bool ALIGN_EPI = false, bool SP2 = false, bool SPLITK = false>
; __device__ __forceinline__ void gemm_phase(PG8_LAS unsigned char* lds, const Gemm g, const Sched& S, const Epi& E) {
;     ...
;             PG8_LDB(B0, 1, 0); PG8_LDB(B1, 1, 1); PG8_SCHED; PG8_LDA(At, 1, 0); PG8_STAGE(PG8_SA(0, 1), a2 + hstep, voffA);
;             PG8_WAIT_V(8); PG8_WAIT_L(0); PG8_BAR; PG8_MMA(0, 0, At, B0); PG8_MMA(0, 1, At, B1); PG8_BAR; PG8_SCHED;
;             PG8_LDA(At, 1, 1); PG8_STAGE(PG8_SB(1, 0), b3, voffB); PG8_STAGE(PG8_SB(1, 1), b3 + hstep, voffB); PG8_STAGE(PG8_SA(1, 0), a3, voffA);
;             PG8_WAIT_V(8); PG8_WAIT_L(0); PG8_BAR; PG8_MMA(1, 0, At, B0); PG8_MMA(1, 1, At, B1); PG8_BAR; PG8_SCHED;
	s_add_i32 s35, 0, 0x18000
	s_add_i32 s43, 0, 0x1c000
	v_add_u32_e32 v142, s35, v198
	v_add_u32_e32 v158, s43, v198
	ds_read_b128 v[130:133], v142
	ds_read_b128 v[134:137], v142 offset:1024
	ds_read_b128 v[138:141], v142 offset:2048
	ds_read_b128 v[142:145], v142 offset:3072
	ds_read_b128 v[146:149], v158
	ds_read_b128 v[150:153], v158 offset:1024
	ds_read_b128 v[154:157], v158 offset:2048
	ds_read_b128 v[158:161], v158 offset:3072
	s_add_u32 s48, s48, 0x40000
	s_addc_u32 s49, s49, 0
	s_mov_b32 m0, s56
	ds_read_b128 v[162:165], v199 offset:32768
	ds_read_b128 v[178:181], v199 offset:33792
	ds_read_b128 v[182:185], v199 offset:34816
	ds_read_b128 v[186:189], v199 offset:35840
	ds_read_b128 v[190:193], v199 offset:36864
	ds_read_b128 v[200:203], v199 offset:37888
	ds_read_b128 v[204:207], v199 offset:38912
	ds_read_b128 v[208:211], v199 offset:39936
	global_load_lds_dwordx4 v168, s[48:49]
	s_mov_b32 m0, s57
	s_nop 0
	global_load_lds_dwordx4 v170, s[48:49]
	s_waitcnt vmcnt(8)
	s_waitcnt lgkmcnt(0)
	s_barrier
	s_waitcnt lgkmcnt(0)
	v_mfma_f32_16x16x32_bf16 v[126:129], v[130:133], v[162:165], v[126:129]
	v_mfma_f32_16x16x32_bf16 v[122:125], v[138:141], v[162:165], v[122:125]
	v_mfma_f32_16x16x32_bf16 v[114:117], v[130:133], v[182:185], v[114:117]
	v_mfma_f32_16x16x32_bf16 v[106:109], v[138:141], v[182:185], v[106:109]
	v_mfma_f32_16x16x32_bf16 v[98:101], v[130:133], v[190:193], v[98:101]
	v_mfma_f32_16x16x32_bf16 v[90:93], v[138:141], v[190:193], v[90:93]
	v_mfma_f32_16x16x32_bf16 v[82:85], v[130:133], v[204:207], v[82:85]
	v_mfma_f32_16x16x32_bf16 v[74:77], v[138:141], v[204:207], v[74:77]
	v_mfma_f32_16x16x32_bf16 v[126:129], v[134:137], v[178:181], v[126:129]
	v_mfma_f32_16x16x32_bf16 v[122:125], v[142:145], v[178:181], v[122:125]
	v_mfma_f32_16x16x32_bf16 v[114:117], v[134:137], v[186:189], v[114:117]
	v_mfma_f32_16x16x32_bf16 v[106:109], v[142:145], v[186:189], v[106:109]
	v_mfma_f32_16x16x32_bf16 v[98:101], v[134:137], v[200:203], v[98:101]
	v_mfma_f32_16x16x32_bf16 v[90:93], v[142:145], v[200:203], v[90:93]
	v_mfma_f32_16x16x32_bf16 v[82:85], v[134:137], v[208:211], v[82:85]
	v_mfma_f32_16x16x32_bf16 v[74:77], v[142:145], v[208:211], v[74:77]
	v_mfma_f32_16x16x32_bf16 v[118:121], v[146:149], v[162:165], v[118:121]
	v_mfma_f32_16x16x32_bf16 v[110:113], v[154:157], v[162:165], v[110:113]
	v_mfma_f32_16x16x32_bf16 v[102:105], v[146:149], v[182:185], v[102:105]
	v_mfma_f32_16x16x32_bf16 v[94:97], v[154:157], v[182:185], v[94:97]
	v_mfma_f32_16x16x32_bf16 v[86:89], v[146:149], v[190:193], v[86:89]
	v_mfma_f32_16x16x32_bf16 v[78:81], v[154:157], v[190:193], v[78:81]
	v_mfma_f32_16x16x32_bf16 v[70:73], v[146:149], v[204:207], v[70:73]
	v_mfma_f32_16x16x32_bf16 v[66:69], v[154:157], v[204:207], v[66:69]
	v_mfma_f32_16x16x32_bf16 v[118:121], v[150:153], v[178:181], v[118:121]
	v_mfma_f32_16x16x32_bf16 v[110:113], v[158:161], v[178:181], v[110:113]
	v_mfma_f32_16x16x32_bf16 v[102:105], v[150:153], v[186:189], v[102:105]
	v_mfma_f32_16x16x32_bf16 v[94:97], v[158:161], v[186:189], v[94:97]
	v_mfma_f32_16x16x32_bf16 v[86:89], v[150:153], v[200:203], v[86:89]
	v_mfma_f32_16x16x32_bf16 v[78:81], v[158:161], v[200:203], v[78:81]
	v_mfma_f32_16x16x32_bf16 v[70:73], v[150:153], v[208:211], v[70:73]
	v_mfma_f32_16x16x32_bf16 v[66:69], v[158:161], v[208:211], v[66:69]
	s_barrier
	s_add_i32 s35, s35, s33
	s_add_u32 s46, s46, 0x80
	s_addc_u32 s47, s47, 0
	s_mov_b32 m0, s35
	ds_read_b128 v[162:165], v199 offset:49152
	ds_read_b128 v[178:181], v199 offset:50176
	ds_read_b128 v[182:185], v199 offset:51200
	ds_read_b128 v[186:189], v199 offset:52224
	ds_read_b128 v[190:193], v199 offset:53248
	ds_read_b128 v[200:203], v199 offset:54272
	ds_read_b128 v[204:207], v199 offset:55296
	ds_read_b128 v[208:211], v199 offset:56320
	global_load_lds_dwordx4 v0, s[46:47]
	s_add_i32 m0, s35, 0x2000
	s_add_i32 s35, s43, s33
	global_load_lds_dwordx4 v172, s[46:47]
	s_add_u32 s46, s46, 0x40000
	s_addc_u32 s47, s47, 0
	s_mov_b32 m0, s35
	s_nop 0
	global_load_lds_dwordx4 v0, s[46:47]
	s_add_i32 m0, s35, 0x2000
	s_nop 0
	global_load_lds_dwordx4 v172, s[46:47]
	s_sub_u32 s76, s48, 0x3ff80
	s_subb_u32 s77, s49, 0
	s_mov_b32 m0, s58
	s_nop 0
	global_load_lds_dwordx4 v168, s[76:77]
	s_mov_b32 m0, s59
	s_nop 0
	global_load_lds_dwordx4 v170, s[76:77]
	s_waitcnt vmcnt(8)
	s_waitcnt lgkmcnt(0)
	s_barrier
	s_waitcnt lgkmcnt(0)
	v_mfma_f32_16x16x32_bf16 v[62:65], v[130:133], v[162:165], v[62:65]
	v_mfma_f32_16x16x32_bf16 v[58:61], v[138:141], v[162:165], v[58:61]
	v_mfma_f32_16x16x32_bf16 v[50:53], v[130:133], v[182:185], v[50:53]
	v_mfma_f32_16x16x32_bf16 v[42:45], v[138:141], v[182:185], v[42:45]
	v_mfma_f32_16x16x32_bf16 v[34:37], v[130:133], v[190:193], v[34:37]
	v_mfma_f32_16x16x32_bf16 v[26:29], v[138:141], v[190:193], v[26:29]
	v_mfma_f32_16x16x32_bf16 v[18:21], v[130:133], v[204:207], v[18:21]
	v_mfma_f32_16x16x32_bf16 v[10:13], v[138:141], v[204:207], v[10:13]
	v_mfma_f32_16x16x32_bf16 v[62:65], v[134:137], v[178:181], v[62:65]
	v_mfma_f32_16x16x32_bf16 v[58:61], v[142:145], v[178:181], v[58:61]
	v_mfma_f32_16x16x32_bf16 v[50:53], v[134:137], v[186:189], v[50:53]
	v_mfma_f32_16x16x32_bf16 v[42:45], v[142:145], v[186:189], v[42:45]
	v_mfma_f32_16x16x32_bf16 v[34:37], v[134:137], v[200:203], v[34:37]
	v_mfma_f32_16x16x32_bf16 v[26:29], v[142:145], v[200:203], v[26:29]
	v_mfma_f32_16x16x32_bf16 v[18:21], v[134:137], v[208:211], v[18:21]
	v_mfma_f32_16x16x32_bf16 v[10:13], v[142:145], v[208:211], v[10:13]
	v_mfma_f32_16x16x32_bf16 v[54:57], v[146:149], v[162:165], v[54:57]
	v_mfma_f32_16x16x32_bf16 v[46:49], v[154:157], v[162:165], v[46:49]
	v_mfma_f32_16x16x32_bf16 v[38:41], v[146:149], v[182:185], v[38:41]
	v_mfma_f32_16x16x32_bf16 v[30:33], v[154:157], v[182:185], v[30:33]
	v_mfma_f32_16x16x32_bf16 v[22:25], v[146:149], v[190:193], v[22:25]
	v_mfma_f32_16x16x32_bf16 v[14:17], v[154:157], v[190:193], v[14:17]
	v_mfma_f32_16x16x32_bf16 v[6:9], v[146:149], v[204:207], v[6:9]
	v_mfma_f32_16x16x32_bf16 v[2:5], v[154:157], v[204:207], v[2:5]
	v_mfma_f32_16x16x32_bf16 v[54:57], v[150:153], v[178:181], v[54:57]
	v_mfma_f32_16x16x32_bf16 v[46:49], v[158:161], v[178:181], v[46:49]
	v_mfma_f32_16x16x32_bf16 v[38:41], v[150:153], v[186:189], v[38:41]
	v_mfma_f32_16x16x32_bf16 v[30:33], v[158:161], v[186:189], v[30:33]
	v_mfma_f32_16x16x32_bf16 v[22:25], v[150:153], v[200:203], v[22:25]
	v_mfma_f32_16x16x32_bf16 v[14:17], v[158:161], v[200:203], v[14:17]
	v_mfma_f32_16x16x32_bf16 v[6:9], v[150:153], v[208:211], v[6:9]
	v_mfma_f32_16x16x32_bf16 v[2:5], v[158:161], v[208:211], v[2:5]
	s_barrier
	s_add_i32 s25, s25, 2
	s_add_u32 s54, s54, 0x100
	s_addc_u32 s55, s55, 0
	s_add_u32 s23, s23, 0x100
	s_addc_u32 s24, s24, 0
	s_cmp_gt_u32 s25, 13
	s_cbranch_scc0 .LBB0_165
	s_and_b64 vcc, exec, s[16:17]
	s_cbranch_vccz .LBB0_168
	s_barrier

; #define PG8_WAIT_V(n) asm volatile("s_waitcnt vmcnt(" #n ")" ::: "memory")
; #define PG8_BAR __builtin_amdgcn_s_barrier()
; template <class Epi, class Sched, bool ALIGN_EPI = false, bool SP2 = false, bool SPLITK = false>
; __device__ __forceinline__ void gemm_phase(PG8_LAS unsigned char* lds, const Gemm g, const Sched& S, const Epi& E) {
;     ...
;     PG8_WAIT_V(0);
;     if constexpr (!ALIGN_EPI) { if (wr == 0) PG8_BAR; }
;     PG8_BAR;
.LBB0_191:
	s_setprio 0
	s_waitcnt vmcnt(0)
	v_readlane_b32 s69, v253, 1
	s_barrier

; #define PG8_BAR __builtin_amdgcn_s_barrier()
;     __host__ __device__ bool next(int i, Unit& u) const {
;         const long L = (long)i * G + c; if (L >= nwg) return false;
;         int wgid = (int)L; { const int q = nwg / NXCD, r = nwg % NXCD, xcd = wgid % NXCD, off = wgid / NXCD; wgid = (xcd < r ? xcd * (q + 1) : r * (q + 1) + (xcd - r) * q) + off; }
;         const int nig = WGM * nN, gid = wgid / nig, fm = gid * WGM, gsz = (nM - fm) < WGM ? (nM - fm) : WGM;
;         u.pm = fm + ((wgid % nig) % gsz); u.pn = (wgid % nig) / gsz; return true;
; template <class Epi, class Sched, bool ALIGN_EPI = false, bool SP2 = false, bool SPLITK = false>
; __device__ __forceinline__ void gemm_phase(PG8_LAS unsigned char* lds, const Gemm g, const Sched& S, const Epi& E) {
;     ...
;     for (int i = 0; i < 2; ++i) { int R, C; stage_rc(tid * 16 + i * 8192, R, C); const int Rb = Epi::PERM ? ((R & ~31) + perm32(R & 31)) : R;
;         voffA[i] = (unsigned)(R * K + C) * 2u; voffB[i] = (unsigned)(Rb * K + C) * 2u; }
;     const size_t kstep = (size_t)(BK * 2);
;     const size_t hstep = (size_t)HALF * K * 2;
;     const size_t tstep = 2 * hstep;
;     const unsigned ldsw = (unsigned)wid * 1024u;
;     const int aoff = lds_byte(wr * 64 + fr, fq * 8), boff = lds_byte(wc * 32 + fr, fq * 8);
;     ...
;     Unit cur, nxt; int ui = 0;
;     if (!S.next(0, cur)) return;
;     f32x4 acc[2][2][4][2];
; #pragma unroll
;     for (int a = 0; a < 2; ++a)
; #pragma unroll
;         for (int b = 0; b < 2; ++b)
; #pragma unroll
;             for (int m = 0; m < 4; ++m)
; #pragma unroll
;                 for (int n = 0; n < 2; ++n) acc[a][b][m][n] = (f32x4){0.f, 0.f, 0.f, 0.f};
;     bf16x8 At[4][2], B0[2][2], B1[2][2];
;     const char* cA = (const char*)g.A + (size_t)cur.pm * tstep; const char* cB = (const char*)g.Bt + (size_t)cur.pn * tstep;
;     const char* cA2 = SPLITK ? (const char*)g.A2 + (size_t)cur.pm * tstep : cA; const char* cB2 = SPLITK ? (const char*)g.Bt2 + (size_t)cur.pn * tstep : cB;
;     ...
;     S.a_ready(cur);
;     if constexpr (SP2) {
;         PG8_STAGE(PG8_SB(0, 0), cB, voffB); PG8_STAGE(PG8_SB(0, 1), cB + hstep, voffB); PG8_STAGE(PG8_SA(0, 0), cA, voffA); PG8_STAGE(PG8_SA(0, 1), cA + hstep, voffA);
;         PG8_STAGE(PG8_SB(1, 0), cB + kstep, voffB); PG8_STAGE(PG8_SA(1, 0), cA + kstep, voffA); PG8_STAGE(PG8_SB(1, 1), cB + hstep + kstep, voffB);
;         if (wr == 1) PG8_BAR;
.LBB0_573:
	s_or_b64 exec, exec, s[16:17]
	v_mov_b32_e32 v3, v244
	s_waitcnt lgkmcnt(0)
	s_barrier
	s_andn2_b64 vcc, exec, s[2:3]
	v_readfirstlane_b32 s12, v3
	s_cbranch_vccnz .LBB0_593
	v_lshlrev_b32_e32 v0, 4, v3
	v_add_u32_e32 v4, 0x2000, v0
	v_ashrrev_i32_e32 v2, 31, v4
	v_lshrrev_b32_e32 v2, 22, v2
	v_add_u32_e32 v2, v4, v2
	v_ashrrev_i32_e32 v2, 10, v2
	v_mul_i32_i24_e32 v5, 0x400, v2
	v_sub_u32_e32 v4, v4, v5
	v_lshrrev_b32_e32 v5, 4, v4
	v_bitop3_b32 v5, v5, v4, 32 bitop3:0x6c
	v_ashrrev_i32_e32 v4, 31, v5
	v_lshrrev_b32_e32 v4, 26, v4
	s_ashr_i32 s17, s12, 6
	v_add_u32_e32 v6, v5, v4
	v_lshlrev_b32_e32 v7, 3, v2
	s_ashr_i32 s4, s12, 8
	s_lshl_b32 s23, s17, 10
	v_readlane_b32 s2, v255, 45
	v_ashrrev_i32_e32 v4, 6, v6
	v_and_b32_e32 v7, -16, v7
	s_add_u32 s33, s2, 0x1600000
	v_readlane_b32 s2, v255, 46
	v_add_u32_e32 v7, v4, v7
	s_addc_u32 s50, s2, 0
	v_and_b32_e32 v8, 3, v4
	s_mov_b32 s2, 0x1fffe0
	v_lshrrev_b32_e32 v9, 2, v7
	v_lshlrev_b32_e32 v10, 1, v7
	v_and_b32_e32 v6, 0xc0, v6
	v_and_or_b32 v8, v7, s2, v8
	v_and_b32_e32 v9, 4, v9
	v_and_b32_e32 v10, 24, v10
	v_sub_u32_e32 v5, v5, v6
	v_or3_b32 v8, v8, v9, v10
	v_lshlrev_b32_e32 v9, 5, v2
	v_ashrrev_i16_sdwa v5, v234, sext(v5) dst_sel:DWORD dst_unused:UNUSED_PAD src0_sel:DWORD src1_sel:BYTE_0
	v_and_b32_e32 v9, 32, v9
	v_bfe_i32 v5, v5, 0, 16
	v_add_lshl_u32 v6, v9, v5, 1
	v_lshl_add_u32 v146, v8, 11, v6
	v_lshl_add_u32 v148, v7, 11, v6
	v_bfe_i32 v6, v3, 27, 1
	v_lshrrev_b32_e32 v6, 22, v6
	v_add_u32_e32 v6, v0, v6
	v_and_b32_e32 v6, 0xfffffc00, v6
	v_sub_u32_e32 v0, v0, v6
	v_lshrrev_b32_e32 v6, 4, v0
	v_ashrrev_i32_e32 v7, 31, v3
	v_bitop3_b32 v0, v6, v0, 32 bitop3:0x6c
	v_lshrrev_b32_e32 v7, 26, v7
	v_ashrrev_i32_e32 v6, 31, v0
	v_add_u32_e32 v7, v3, v7
	v_lshrrev_b32_e32 v6, 26, v6
	v_ashrrev_i32_e32 v7, 6, v7
	v_add_u32_e32 v8, v0, v6
	v_lshlrev_b32_e32 v9, 3, v7
	v_ashrrev_i32_e32 v6, 6, v8
	v_and_b32_e32 v9, -16, v9
	v_add_u32_e32 v9, v6, v9
	v_and_b32_e32 v10, 3, v6
	v_and_or_b32 v10, v9, s2, v10
	s_ashr_i32 s2, s1, 31
	s_lshr_b32 s2, s2, 29
	s_add_i32 s2, s1, s2
	s_ashr_i32 s3, s2, 3
	s_and_b32 s2, s2, -8
	s_sub_i32 s2, s1, s2
	s_cmp_lt_i32 s2, 0
	s_movk_i32 s16, 0xb1
	s_cselect_b32 s16, s16, 0xb0
	s_mul_i32 s2, s2, s16
	s_add_i32 s2, s2, s3
	s_mul_hi_i32 s3, s2, 0x2e8ba2e9
	s_lshr_b32 s16, s3, 31
	s_ashr_i32 s3, s3, 5
	s_add_i32 s3, s3, s16
	s_lshl_b32 s18, s3, 3
	s_mulk_i32 s3, 0xb0
	s_sub_i32 s2, s2, s3
	s_bfe_u32 s3, s2, 0x3001c
	s_add_i32 s3, s2, s3
	s_sext_i32_i16 s16, s3
	s_and_b32 s3, s3, 0xfff8
	s_sub_i32 s2, s2, s3
	s_sext_i32_i16 s2, s2
	v_lshrrev_b32_e32 v11, 2, v9
	v_lshlrev_b32_e32 v12, 1, v9
	v_and_b32_e32 v8, 0xc0, v8
	s_lshr_b32 s16, s16, 3
	s_add_i32 s40, s18, s2
	v_and_b32_e32 v11, 4, v11
	v_and_b32_e32 v12, 24, v12
	v_sub_u32_e32 v0, v0, v8
	s_ashr_i32 s41, s40, 31
	s_bfe_i64 s[18:19], s[16:17], 0x100000
	v_or3_b32 v10, v10, v11, v12
	v_lshlrev_b32_e32 v11, 5, v7
	v_ashrrev_i16_sdwa v0, v234, sext(v0) dst_sel:DWORD dst_unused:UNUSED_PAD src0_sel:DWORD src1_sel:BYTE_0
	s_lshl_b64 s[2:3], s[40:41], 19
	s_lshl_b64 s[18:19], s[18:19], 19
	v_and_b32_e32 v11, 32, v11
	v_bfe_i32 v8, v0, 0, 16
	s_add_u32 s46, s33, s18
	v_add_lshl_u32 v11, v11, v8, 1
	s_addc_u32 s47, s50, s19
	s_add_i32 s51, s23, 0
	v_lshl_add_u32 v0, v10, 11, v11
	s_add_i32 m0, s51, 0x10000
	v_lshl_add_u32 v150, v9, 11, v11
	global_load_lds_dwordx4 v0, s[46:47]
	s_add_i32 m0, s51, 0x12000
	s_add_u32 s18, s46, 0x40000
	global_load_lds_dwordx4 v146, s[46:47]
	s_addc_u32 s19, s47, 0
	s_add_i32 m0, s51, 0x14000
	v_lshl_add_u64 v[10:11], s[46:47], 0, v[0:1]
	global_load_lds_dwordx4 v0, s[18:19]
	s_add_i32 m0, s51, 0x16000
	s_add_u32 s42, s82, s2
	s_addc_u32 s43, s83, s3
	s_add_i32 s52, s51, 0x2000
	global_load_lds_dwordx4 v146, s[18:19]
	s_mov_b32 m0, s51
	s_add_u32 s2, s42, 0x40000
	global_load_lds_dwordx4 v150, s[42:43]
	s_mov_b32 m0, s52
	s_addc_u32 s3, s43, 0
	s_add_i32 s53, s51, 0x4000
	global_load_lds_dwordx4 v148, s[42:43]
	s_mov_b32 m0, s53
	s_add_i32 s54, s51, 0x6000
	v_mov_b32_e32 v147, v1
	global_load_lds_dwordx4 v150, s[2:3]
	s_mov_b32 m0, s54
	v_lshl_add_u64 v[12:13], s[46:47], 0, v[146:147]
	v_mov_b32_e32 v151, v1
	global_load_lds_dwordx4 v148, s[2:3]
	s_add_i32 m0, s51, 0x18000
	v_lshl_add_u64 v[10:11], v[10:11], 0, s[70:71]
	v_lshl_add_u64 v[14:15], s[42:43], 0, v[150:151]
	v_mov_b32_e32 v149, v1
	global_load_lds_dwordx4 v[10:11], off
	v_lshl_add_u64 v[10:11], v[12:13], 0, s[70:71]
	s_add_i32 m0, s51, 0x1a000
	s_add_i32 s55, s51, 0x8000
	v_lshl_add_u64 v[16:17], s[42:43], 0, v[148:149]
	global_load_lds_dwordx4 v[10:11], off
	v_lshl_add_u64 v[10:11], v[14:15], 0, s[70:71]
	s_mov_b32 m0, s55
	s_add_i32 s56, s51, 0xa000
	global_load_lds_dwordx4 v[10:11], off
	v_lshl_add_u64 v[10:11], v[16:17], 0, s[70:71]
	s_mov_b32 m0, s56
	s_add_u32 s2, s46, 0x40080
	global_load_lds_dwordx4 v[10:11], off
	s_addc_u32 s3, s47, 0
	s_add_i32 m0, s51, 0x1c000
	s_nop 0
	global_load_lds_dwordx4 v0, s[2:3]
	s_add_i32 m0, s51, 0x1e000
	s_cmp_eq_u32 s4, 1
	global_load_lds_dwordx4 v146, s[2:3]
	s_cselect_b64 s[2:3], -1, 0
	s_cmp_lg_u32 s4, 1
	s_cbranch_scc1 .LBB0_576
	s_setprio 1
	s_barrier

; #define PG8_STAGE(bufoff, gbase, voff) do { _Pragma("unroll") for (int _i = 0; _i < 2; ++_i) \
;         __builtin_amdgcn_global_load_lds((const unsigned*)((const char*)(gbase) + (voff)[_i]), (PG8_LAS unsigned*)(lds + (bufoff) + ldsw + _i * 8192), 16, 0, 0); } while (0)
; #define PG8_LDA(dst, b, h) do { _Pragma("unroll") for (int m = 0; m < 4; ++m) _Pragma("unroll") for (int k = 0; k < 2; ++k) dst[m][k] = *(const PG8_LAS bf16x8*)(lds + PG8_SA(b, h) + aoff + m * 2048 + k * 1024); } while (0)
; #define PG8_LDB(dst, b, h) do { _Pragma("unroll") for (int n = 0; n < 2; ++n) _Pragma("unroll") for (int k = 0; k < 2; ++k) dst[n][k] = *(const PG8_LAS bf16x8*)(lds + PG8_SB(b, h) + boff + n * 2048 + k * 1024); } while (0)
; #define PG8_MMA(ai, bj, At, Bt) do { __builtin_amdgcn_s_setprio(1); _Pragma("unroll") for (int m = 0; m < 4; ++m) _Pragma("unroll") for (int n = 0; n < 2; ++n) _Pragma("unroll") for (int k = 0; k < 2; ++k) \
;         acc[ai][bj][m][n] = __builtin_amdgcn_mfma_f32_16x16x32_bf16(Bt[n][k], At[m][k], acc[ai][bj][m][n], 0, 0, 0); __builtin_amdgcn_s_setprio(0); } while (0)
; #define PG8_WAIT_V(n) asm volatile("s_waitcnt vmcnt(" #n ")" ::: "memory")
; #define PG8_WAIT_L(n) asm volatile("s_waitcnt lgkmcnt(" #n ")" ::: "memory")
; #define PG8_BAR __builtin_amdgcn_s_barrier()
; #define PG8_SCHED __builtin_amdgcn_sched_barrier(0)
; template <class Epi, class Sched, bool ALIGN_EPI = false, bool SP2 = false, bool SPLITK = false>
; __device__ __forceinline__ void gemm_phase(PG8_LAS unsigned char* lds, const Gemm g, const Sched& S, const Epi& E) {
;     ...
;             PG8_LDB(B0, 0, 0); PG8_LDB(B1, 0, 1); PG8_SCHED; PG8_LDA(At, 0, 0); PG8_STAGE(PG8_SA(1, 1), a1 + hstep, voffA);
;             PG8_WAIT_V(8); PG8_WAIT_L(0); PG8_BAR; PG8_MMA(0, 0, At, B0); PG8_MMA(0, 1, At, B1); PG8_BAR; PG8_SCHED;
;             PG8_LDA(At, 0, 1); PG8_STAGE(PG8_SB(0, 0), b2, voffB); PG8_STAGE(PG8_SB(0, 1), b2 + hstep, voffB); PG8_STAGE(PG8_SA(0, 0), a2, voffA);
;             PG8_WAIT_V(8); PG8_WAIT_L(0); PG8_BAR; PG8_MMA(1, 0, At, B0); PG8_MMA(1, 1, At, B1); PG8_BAR; PG8_SCHED;
.LBB0_582:
	s_add_u32 s46, s42, 0xfffc0080
	s_addc_u32 s47, s43, -1
	s_add_i32 s64, 0, 0x10000
	s_cmp_eq_u32 s45, 12
	s_cselect_b32 s49, s4, s47
	s_cselect_b32 s48, s12, s46
	s_cselect_b32 s47, s19, s41
	s_cselect_b32 s46, s21, s25
	s_add_i32 s68, 0, 0x14000
	v_add_u32_e32 v142, s64, v181
	v_add_u32_e32 v168, s68, v181
	ds_read_b128 v[130:133], v142
	ds_read_b128 v[134:137], v142 offset:1024
	ds_read_b128 v[138:141], v142 offset:2048
	ds_read_b128 v[142:145], v142 offset:3072
	ds_read_b128 v[156:159], v168
	ds_read_b128 v[160:163], v168 offset:1024
	ds_read_b128 v[164:167], v168 offset:2048
	ds_read_b128 v[170:173], v168 offset:3072
	s_add_i32 m0, s51, 0xc000
	ds_read_b128 v[176:179], v186
	ds_read_b128 v[182:185], v186 offset:1024
	ds_read_b128 v[188:191], v186 offset:2048
	ds_read_b128 v[192:195], v186 offset:3072
	ds_read_b128 v[196:199], v186 offset:4096
	ds_read_b128 v[200:203], v186 offset:5120
	ds_read_b128 v[204:207], v186 offset:6144
	ds_read_b128 v[208:211], v186 offset:7168
	global_load_lds_dwordx4 v152, s[42:43]
	s_add_i32 m0, s51, 0xe000
	s_nop 0
	global_load_lds_dwordx4 v154, s[42:43]
	s_waitcnt vmcnt(8)
	s_waitcnt lgkmcnt(0)
	s_barrier
	s_waitcnt lgkmcnt(0)
	v_mfma_f32_16x16x32_bf16 v[126:129], v[130:133], v[176:179], v[126:129]
	v_mfma_f32_16x16x32_bf16 v[118:121], v[138:141], v[176:179], v[118:121]
	v_mfma_f32_16x16x32_bf16 v[110:113], v[130:133], v[188:191], v[110:113]
	v_mfma_f32_16x16x32_bf16 v[102:105], v[138:141], v[188:191], v[102:105]
	v_mfma_f32_16x16x32_bf16 v[94:97], v[130:133], v[196:199], v[94:97]
	v_mfma_f32_16x16x32_bf16 v[86:89], v[138:141], v[196:199], v[86:89]
	v_mfma_f32_16x16x32_bf16 v[78:81], v[130:133], v[204:207], v[78:81]
	v_mfma_f32_16x16x32_bf16 v[70:73], v[138:141], v[204:207], v[70:73]
	v_mfma_f32_16x16x32_bf16 v[126:129], v[134:137], v[182:185], v[126:129]
	v_mfma_f32_16x16x32_bf16 v[118:121], v[142:145], v[182:185], v[118:121]
	v_mfma_f32_16x16x32_bf16 v[110:113], v[134:137], v[192:195], v[110:113]
	v_mfma_f32_16x16x32_bf16 v[102:105], v[142:145], v[192:195], v[102:105]
	v_mfma_f32_16x16x32_bf16 v[94:97], v[134:137], v[200:203], v[94:97]
	v_mfma_f32_16x16x32_bf16 v[86:89], v[142:145], v[200:203], v[86:89]
	v_mfma_f32_16x16x32_bf16 v[78:81], v[134:137], v[208:211], v[78:81]
	v_mfma_f32_16x16x32_bf16 v[70:73], v[142:145], v[208:211], v[70:73]
	v_mfma_f32_16x16x32_bf16 v[122:125], v[156:159], v[176:179], v[122:125]
	v_mfma_f32_16x16x32_bf16 v[114:117], v[164:167], v[176:179], v[114:117]
	v_mfma_f32_16x16x32_bf16 v[106:109], v[156:159], v[188:191], v[106:109]
	v_mfma_f32_16x16x32_bf16 v[98:101], v[164:167], v[188:191], v[98:101]
	v_mfma_f32_16x16x32_bf16 v[90:93], v[156:159], v[196:199], v[90:93]
	v_mfma_f32_16x16x32_bf16 v[82:85], v[164:167], v[196:199], v[82:85]
	v_mfma_f32_16x16x32_bf16 v[74:77], v[156:159], v[204:207], v[74:77]
	v_mfma_f32_16x16x32_bf16 v[66:69], v[164:167], v[204:207], v[66:69]
	v_mfma_f32_16x16x32_bf16 v[122:125], v[160:163], v[182:185], v[122:125]
	v_mfma_f32_16x16x32_bf16 v[114:117], v[170:173], v[182:185], v[114:117]
	v_mfma_f32_16x16x32_bf16 v[106:109], v[160:163], v[192:195], v[106:109]
	v_mfma_f32_16x16x32_bf16 v[98:101], v[170:173], v[192:195], v[98:101]
	v_mfma_f32_16x16x32_bf16 v[90:93], v[160:163], v[200:203], v[90:93]
	v_mfma_f32_16x16x32_bf16 v[82:85], v[170:173], v[200:203], v[82:85]
	v_mfma_f32_16x16x32_bf16 v[74:77], v[160:163], v[208:211], v[74:77]
	v_mfma_f32_16x16x32_bf16 v[66:69], v[170:173], v[208:211], v[66:69]
	s_barrier
	s_add_i32 s64, s64, s23
	s_mov_b32 m0, s64
	ds_read_b128 v[176:179], v186 offset:16384
	ds_read_b128 v[182:185], v186 offset:17408
	ds_read_b128 v[188:191], v186 offset:18432
	ds_read_b128 v[192:195], v186 offset:19456
	ds_read_b128 v[196:199], v186 offset:20480
	ds_read_b128 v[200:203], v186 offset:21504
	ds_read_b128 v[204:207], v186 offset:22528
	ds_read_b128 v[208:211], v186 offset:23552
	global_load_lds_dwordx4 v0, s[46:47]
	s_add_i32 m0, s64, 0x2000
	s_add_u32 s64, s46, 0x40000
	s_addc_u32 s65, s47, 0
	s_add_i32 s68, s68, s23
	global_load_lds_dwordx4 v146, s[46:47]
	s_mov_b32 m0, s68
	s_nop 0
	global_load_lds_dwordx4 v0, s[64:65]
	s_add_i32 m0, s68, 0x2000
	s_nop 0
	global_load_lds_dwordx4 v146, s[64:65]
	s_mov_b32 m0, s51
	s_nop 0
	global_load_lds_dwordx4 v150, s[48:49]
	s_mov_b32 m0, s52
	s_nop 0
	global_load_lds_dwordx4 v148, s[48:49]
	s_waitcnt vmcnt(8)
	s_waitcnt lgkmcnt(0)
	s_barrier
	s_waitcnt lgkmcnt(0)
	v_mfma_f32_16x16x32_bf16 v[62:65], v[130:133], v[176:179], v[62:65]
	v_mfma_f32_16x16x32_bf16 v[54:57], v[138:141], v[176:179], v[54:57]
	v_mfma_f32_16x16x32_bf16 v[46:49], v[130:133], v[188:191], v[46:49]
	v_mfma_f32_16x16x32_bf16 v[38:41], v[138:141], v[188:191], v[38:41]
	v_mfma_f32_16x16x32_bf16 v[30:33], v[130:133], v[196:199], v[30:33]
	v_mfma_f32_16x16x32_bf16 v[22:25], v[138:141], v[196:199], v[22:25]
	v_mfma_f32_16x16x32_bf16 v[14:17], v[130:133], v[204:207], v[14:17]
	v_mfma_f32_16x16x32_bf16 v[6:9], v[138:141], v[204:207], v[6:9]
	v_mfma_f32_16x16x32_bf16 v[62:65], v[134:137], v[182:185], v[62:65]
	v_mfma_f32_16x16x32_bf16 v[54:57], v[142:145], v[182:185], v[54:57]
	v_mfma_f32_16x16x32_bf16 v[46:49], v[134:137], v[192:195], v[46:49]
	v_mfma_f32_16x16x32_bf16 v[38:41], v[142:145], v[192:195], v[38:41]
	v_mfma_f32_16x16x32_bf16 v[30:33], v[134:137], v[200:203], v[30:33]
	v_mfma_f32_16x16x32_bf16 v[22:25], v[142:145], v[200:203], v[22:25]
	v_mfma_f32_16x16x32_bf16 v[14:17], v[134:137], v[208:211], v[14:17]
	v_mfma_f32_16x16x32_bf16 v[6:9], v[142:145], v[208:211], v[6:9]
	v_mfma_f32_16x16x32_bf16 v[58:61], v[156:159], v[176:179], v[58:61]
	v_mfma_f32_16x16x32_bf16 v[50:53], v[164:167], v[176:179], v[50:53]
	v_mfma_f32_16x16x32_bf16 v[42:45], v[156:159], v[188:191], v[42:45]
	v_mfma_f32_16x16x32_bf16 v[34:37], v[164:167], v[188:191], v[34:37]
	v_mfma_f32_16x16x32_bf16 v[26:29], v[156:159], v[196:199], v[26:29]
	v_mfma_f32_16x16x32_bf16 v[18:21], v[164:167], v[196:199], v[18:21]
	v_mfma_f32_16x16x32_bf16 v[10:13], v[156:159], v[204:207], v[10:13]
	v_mfma_f32_16x16x32_bf16 v[2:5], v[164:167], v[204:207], v[2:5]
	v_mfma_f32_16x16x32_bf16 v[58:61], v[160:163], v[182:185], v[58:61]
	v_mfma_f32_16x16x32_bf16 v[50:53], v[170:173], v[182:185], v[50:53]
	v_mfma_f32_16x16x32_bf16 v[42:45], v[160:163], v[192:195], v[42:45]
	v_mfma_f32_16x16x32_bf16 v[34:37], v[170:173], v[192:195], v[34:37]
	v_mfma_f32_16x16x32_bf16 v[26:29], v[160:163], v[200:203], v[26:29]
	v_mfma_f32_16x16x32_bf16 v[18:21], v[170:173], v[200:203], v[18:21]
	v_mfma_f32_16x16x32_bf16 v[10:13], v[160:163], v[208:211], v[10:13]
	v_mfma_f32_16x16x32_bf16 v[2:5], v[170:173], v[208:211], v[2:5]
	s_barrier
; #define PG8_STAGE(bufoff, gbase, voff) do { _Pragma("unroll") for (int _i = 0; _i < 2; ++_i) \
;         __builtin_amdgcn_global_load_lds((const unsigned*)((const char*)(gbase) + (voff)[_i]), (PG8_LAS unsigned*)(lds + (bufoff) + ldsw + _i * 8192), 16, 0, 0); } while (0)
; #define PG8_LDA(dst, b, h) do { _Pragma("unroll") for (int m = 0; m < 4; ++m) _Pragma("unroll") for (int k = 0; k < 2; ++k) dst[m][k] = *(const PG8_LAS bf16x8*)(lds + PG8_SA(b, h) + aoff + m * 2048 + k * 1024); } while (0)
; #define PG8_LDB(dst, b, h) do { _Pragma("unroll") for (int n = 0; n < 2; ++n) _Pragma("unroll") for (int k = 0; k < 2; ++k) dst[n][k] = *(const PG8_LAS bf16x8*)(lds + PG8_SB(b, h) + boff + n * 2048 + k * 1024); } while (0)
; #define PG8_MMA(ai, bj, At, Bt) do { __builtin_amdgcn_s_setprio(1); _Pragma("unroll") for (int m = 0; m < 4; ++m) _Pragma("unroll") for (int n = 0; n < 2; ++n) _Pragma("unroll") for (int k = 0; k < 2; ++k) \
;         acc[ai][bj][m][n] = __builtin_amdgcn_mfma_f32_16x16x32_bf16(Bt[n][k], At[m][k], acc[ai][bj][m][n], 0, 0, 0); __builtin_amdgcn_s_setprio(0); } while (0)
; #define PG8_WAIT_V(n) asm volatile("s_waitcnt vmcnt(" #n ")" ::: "memory")
; #define PG8_WAIT_L(n) asm volatile("s_waitcnt lgkmcnt(" #n ")" ::: "memory")
; #define PG8_BAR __builtin_amdgcn_s_barrier()
; #define PG8_SCHED __builtin_amdgcn_sched_barrier(0)
; template <class Epi, class Sched, bool ALIGN_EPI = false, bool SP2 = false, bool SPLITK = false>
; __device__ __forceinline__ void gemm_phase(PG8_LAS unsigned char* lds, const Gemm g, const Sched& S, const Epi& E) {
;     ...
;             PG8_LDB(B0, 1, 0); PG8_LDB(B1, 1, 1); PG8_SCHED; PG8_LDA(At, 1, 0); PG8_STAGE(PG8_SA(0, 1), a2 + hstep, voffA);
;             PG8_WAIT_V(8); PG8_WAIT_L(0); PG8_BAR; PG8_MMA(0, 0, At, B0); PG8_MMA(0, 1, At, B1); PG8_BAR; PG8_SCHED;
;             PG8_LDA(At, 1, 1); PG8_STAGE(PG8_SB(1, 0), b3, voffB); PG8_STAGE(PG8_SB(1, 1), b3 + hstep, voffB); PG8_STAGE(PG8_SA(1, 0), a3, voffA);
;             PG8_WAIT_V(8); PG8_WAIT_L(0); PG8_BAR; PG8_MMA(1, 0, At, B0); PG8_MMA(1, 1, At, B1); PG8_BAR; PG8_SCHED;
	s_add_i32 s64, 0, 0x18000
	s_add_i32 s65, 0, 0x1c000
	v_add_u32_e32 v142, s64, v181
	v_add_u32_e32 v168, s65, v181
	ds_read_b128 v[130:133], v142
	ds_read_b128 v[134:137], v142 offset:1024
	ds_read_b128 v[138:141], v142 offset:2048
	ds_read_b128 v[142:145], v142 offset:3072
	ds_read_b128 v[156:159], v168
	ds_read_b128 v[160:163], v168 offset:1024
	ds_read_b128 v[164:167], v168 offset:2048
	ds_read_b128 v[170:173], v168 offset:3072
	s_add_u32 vcc_lo, s48, 0x80
	s_addc_u32 vcc_hi, s49, 0
	s_add_u32 s48, s48, 0x40000
	s_addc_u32 s49, s49, 0
	s_mov_b32 m0, s53
	ds_read_b128 v[176:179], v186 offset:32768
	ds_read_b128 v[182:185], v186 offset:33792
	ds_read_b128 v[188:191], v186 offset:34816
	ds_read_b128 v[192:195], v186 offset:35840
	ds_read_b128 v[196:199], v186 offset:36864
	ds_read_b128 v[200:203], v186 offset:37888
	ds_read_b128 v[204:207], v186 offset:38912
	ds_read_b128 v[208:211], v186 offset:39936
	global_load_lds_dwordx4 v150, s[48:49]
	s_mov_b32 m0, s54
	s_nop 0
	global_load_lds_dwordx4 v148, s[48:49]
	s_waitcnt vmcnt(8)
	s_waitcnt lgkmcnt(0)
	s_barrier
	s_waitcnt lgkmcnt(0)
	v_mfma_f32_16x16x32_bf16 v[126:129], v[130:133], v[176:179], v[126:129]
	v_mfma_f32_16x16x32_bf16 v[118:121], v[138:141], v[176:179], v[118:121]
	v_mfma_f32_16x16x32_bf16 v[110:113], v[130:133], v[188:191], v[110:113]
	v_mfma_f32_16x16x32_bf16 v[102:105], v[138:141], v[188:191], v[102:105]
	v_mfma_f32_16x16x32_bf16 v[94:97], v[130:133], v[196:199], v[94:97]
	v_mfma_f32_16x16x32_bf16 v[86:89], v[138:141], v[196:199], v[86:89]
	v_mfma_f32_16x16x32_bf16 v[78:81], v[130:133], v[204:207], v[78:81]
	v_mfma_f32_16x16x32_bf16 v[70:73], v[138:141], v[204:207], v[70:73]
	v_mfma_f32_16x16x32_bf16 v[126:129], v[134:137], v[182:185], v[126:129]
	v_mfma_f32_16x16x32_bf16 v[118:121], v[142:145], v[182:185], v[118:121]
	v_mfma_f32_16x16x32_bf16 v[110:113], v[134:137], v[192:195], v[110:113]
	v_mfma_f32_16x16x32_bf16 v[102:105], v[142:145], v[192:195], v[102:105]
	v_mfma_f32_16x16x32_bf16 v[94:97], v[134:137], v[200:203], v[94:97]
	v_mfma_f32_16x16x32_bf16 v[86:89], v[142:145], v[200:203], v[86:89]
	v_mfma_f32_16x16x32_bf16 v[78:81], v[134:137], v[208:211], v[78:81]
	v_mfma_f32_16x16x32_bf16 v[70:73], v[142:145], v[208:211], v[70:73]
	v_mfma_f32_16x16x32_bf16 v[122:125], v[156:159], v[176:179], v[122:125]
	v_mfma_f32_16x16x32_bf16 v[114:117], v[164:167], v[176:179], v[114:117]
	v_mfma_f32_16x16x32_bf16 v[106:109], v[156:159], v[188:191], v[106:109]
	v_mfma_f32_16x16x32_bf16 v[98:101], v[164:167], v[188:191], v[98:101]
	v_mfma_f32_16x16x32_bf16 v[90:93], v[156:159], v[196:199], v[90:93]
	v_mfma_f32_16x16x32_bf16 v[82:85], v[164:167], v[196:199], v[82:85]
	v_mfma_f32_16x16x32_bf16 v[74:77], v[156:159], v[204:207], v[74:77]
	v_mfma_f32_16x16x32_bf16 v[66:69], v[164:167], v[204:207], v[66:69]
	v_mfma_f32_16x16x32_bf16 v[122:125], v[160:163], v[182:185], v[122:125]
	v_mfma_f32_16x16x32_bf16 v[114:117], v[170:173], v[182:185], v[114:117]
	v_mfma_f32_16x16x32_bf16 v[106:109], v[160:163], v[192:195], v[106:109]
	v_mfma_f32_16x16x32_bf16 v[98:101], v[170:173], v[192:195], v[98:101]
	v_mfma_f32_16x16x32_bf16 v[90:93], v[160:163], v[200:203], v[90:93]
	v_mfma_f32_16x16x32_bf16 v[82:85], v[170:173], v[200:203], v[82:85]
	v_mfma_f32_16x16x32_bf16 v[74:77], v[160:163], v[208:211], v[74:77]
	v_mfma_f32_16x16x32_bf16 v[66:69], v[170:173], v[208:211], v[66:69]
	s_barrier
	s_add_i32 s48, s64, s23
	s_add_u32 s46, s46, 0x80
	s_addc_u32 s47, s47, 0
	s_mov_b32 m0, s48
	ds_read_b128 v[176:179], v186 offset:49152
	ds_read_b128 v[182:185], v186 offset:50176
	ds_read_b128 v[188:191], v186 offset:51200
	ds_read_b128 v[192:195], v186 offset:52224
	ds_read_b128 v[196:199], v186 offset:53248
	ds_read_b128 v[200:203], v186 offset:54272
	ds_read_b128 v[204:207], v186 offset:55296
	ds_read_b128 v[208:211], v186 offset:56320
	global_load_lds_dwordx4 v0, s[46:47]
	s_add_i32 m0, s48, 0x2000
	s_add_i32 s48, s65, s23
	global_load_lds_dwordx4 v146, s[46:47]
	s_add_u32 s46, s46, 0x40000
	s_addc_u32 s47, s47, 0
	s_mov_b32 m0, s48
	s_nop 0
	global_load_lds_dwordx4 v0, s[46:47]
	s_add_i32 m0, s48, 0x2000
	s_nop 0
	global_load_lds_dwordx4 v146, s[46:47]
	s_mov_b32 m0, s55
	s_nop 0
	global_load_lds_dwordx4 v150, vcc
	s_mov_b32 m0, s56
	s_nop 0
	global_load_lds_dwordx4 v148, vcc
	s_waitcnt vmcnt(8)
	s_waitcnt lgkmcnt(0)
	s_barrier
	s_waitcnt lgkmcnt(0)
	v_mfma_f32_16x16x32_bf16 v[62:65], v[130:133], v[176:179], v[62:65]
	v_mfma_f32_16x16x32_bf16 v[54:57], v[138:141], v[176:179], v[54:57]
	v_mfma_f32_16x16x32_bf16 v[46:49], v[130:133], v[188:191], v[46:49]
	v_mfma_f32_16x16x32_bf16 v[38:41], v[138:141], v[188:191], v[38:41]
	v_mfma_f32_16x16x32_bf16 v[30:33], v[130:133], v[196:199], v[30:33]
	v_mfma_f32_16x16x32_bf16 v[22:25], v[138:141], v[196:199], v[22:25]
	v_mfma_f32_16x16x32_bf16 v[14:17], v[130:133], v[204:207], v[14:17]
	v_mfma_f32_16x16x32_bf16 v[6:9], v[138:141], v[204:207], v[6:9]
	v_mfma_f32_16x16x32_bf16 v[62:65], v[134:137], v[182:185], v[62:65]
	v_mfma_f32_16x16x32_bf16 v[54:57], v[142:145], v[182:185], v[54:57]
	v_mfma_f32_16x16x32_bf16 v[46:49], v[134:137], v[192:195], v[46:49]
	v_mfma_f32_16x16x32_bf16 v[38:41], v[142:145], v[192:195], v[38:41]
	v_mfma_f32_16x16x32_bf16 v[30:33], v[134:137], v[200:203], v[30:33]
	v_mfma_f32_16x16x32_bf16 v[22:25], v[142:145], v[200:203], v[22:25]
	v_mfma_f32_16x16x32_bf16 v[14:17], v[134:137], v[208:211], v[14:17]
	v_mfma_f32_16x16x32_bf16 v[6:9], v[142:145], v[208:211], v[6:9]
	v_mfma_f32_16x16x32_bf16 v[58:61], v[156:159], v[176:179], v[58:61]
	v_mfma_f32_16x16x32_bf16 v[50:53], v[164:167], v[176:179], v[50:53]
	v_mfma_f32_16x16x32_bf16 v[42:45], v[156:159], v[188:191], v[42:45]
	v_mfma_f32_16x16x32_bf16 v[34:37], v[164:167], v[188:191], v[34:37]
	v_mfma_f32_16x16x32_bf16 v[26:29], v[156:159], v[196:199], v[26:29]
	v_mfma_f32_16x16x32_bf16 v[18:21], v[164:167], v[196:199], v[18:21]
	v_mfma_f32_16x16x32_bf16 v[10:13], v[156:159], v[204:207], v[10:13]
	v_mfma_f32_16x16x32_bf16 v[2:5], v[164:167], v[204:207], v[2:5]
	v_mfma_f32_16x16x32_bf16 v[58:61], v[160:163], v[182:185], v[58:61]
	v_mfma_f32_16x16x32_bf16 v[50:53], v[170:173], v[182:185], v[50:53]
	v_mfma_f32_16x16x32_bf16 v[42:45], v[160:163], v[192:195], v[42:45]
	v_mfma_f32_16x16x32_bf16 v[34:37], v[170:173], v[192:195], v[34:37]
	v_mfma_f32_16x16x32_bf16 v[26:29], v[160:163], v[200:203], v[26:29]
	v_mfma_f32_16x16x32_bf16 v[18:21], v[170:173], v[200:203], v[18:21]
	v_mfma_f32_16x16x32_bf16 v[10:13], v[160:163], v[208:211], v[10:13]
	v_mfma_f32_16x16x32_bf16 v[2:5], v[170:173], v[208:211], v[2:5]
	s_barrier
	s_add_i32 s45, s45, 2
	s_add_u32 s42, s42, 0x100
	s_addc_u32 s43, s43, 0
	s_add_u32 s25, s25, 0x100
	s_addc_u32 s41, s41, 0
	s_cmp_gt_u32 s45, 13
	s_cbranch_scc0 .LBB0_582
	s_and_b64 vcc, exec, s[16:17]
	s_cbranch_vccz .LBB0_585
	s_barrier

; #define PG8_WAIT_V(n) asm volatile("s_waitcnt vmcnt(" #n ")" ::: "memory")
; #define PG8_BAR __builtin_amdgcn_s_barrier()
; template <class Epi, class Sched, bool ALIGN_EPI = false, bool SP2 = false, bool SPLITK = false>
; __device__ __forceinline__ void gemm_phase(PG8_LAS unsigned char* lds, const Gemm g, const Sched& S, const Epi& E) {
;     ...
;     PG8_WAIT_V(0);
;     if constexpr (!ALIGN_EPI) { if (wr == 0) PG8_BAR; }
;     PG8_BAR;
.LBB0_592:
	s_setprio 0
	s_waitcnt vmcnt(0)
	s_barrier
